# one static s_setprio 1 for waves 4-7 for the whole attention phase (reset to 0 at its end)
# speedup vs baseline: 1.0528x; 1.0112x over previous
; #define LAS __attribute__((address_space(3)))
;     __device__ __forceinline__ const float* in(int k) const { return (const float*)(const GAS float*)ld(k); }
;     __device__ __forceinline__ unsigned char* ws() const { return (unsigned char*)(GAS unsigned char*)ld(26); }
; template <int VAR> __device__ __forceinline__ void attn_phase(LAS unsigned char* lds, const PTab& P, const int wid_s) {
;     const int tid_ = phase_tid(wid_s);
;     const int tid = tid_, wave = __builtin_amdgcn_readfirstlane(tid >> 6), lane = tid & 63, r = lane & 31, h = lane >> 5;
;     unsigned char* ws = P.ws();
;     const bf16_t* qd = (const bf16_t*)(ws + WS_QD); const bf16_t* kd = (const bf16_t*)(ws + WS_KD); const bf16_t* vtd = (const bf16_t*)(ws + WS_VTD);
;     const bf16_t* qm = (const bf16_t*)(ws + WS_QM); const bf16_t* km = (const bf16_t*)(ws + WS_KM); const bf16_t* vtm = (const bf16_t*)(ws + WS_VTM);
;     bf16_t* mix = (bf16_t*)(ws + WS_ACT);
;     const float d1 = wave_sum(P.in(9)[lane] * P.in(10)[lane]), d2 = wave_sum(P.in(11)[lane] * P.in(12)[lane]);
;     const float lam = __expf(d1) - __expf(d2) + LAM_INIT;
;     const float* gsub = P.in(13);
;     const int grp = (wave ^ (wave >> 2)) & 1;
;     const int G = gridDim.x, c = blockIdx.x;
;     constexpr int NPI = 2048, NITEMS = NPI + 64;
;     const bool xcd_order = (G == 256);
;     const int rounds = xcd_order ? 9 : (NITEMS + G - 1) / G;
.LBB0_717:
	s_or_b64 exec, exec, s[0:1]
	s_cmp_lt_u32 s66, 0x100
	s_cbranch_scc1 .Lmy_att_noprio
	s_setprio 1
.Lmy_att_noprio:
	s_add_i32 s0, 0, 0x204d0
	v_mov_b32_e32 v1, s0
	s_add_i32 s0, 0, 0x20448
	s_waitcnt lgkmcnt(0)
	s_barrier
	v_mbcnt_lo_u32_b32 v0, -1, 0
	v_mbcnt_hi_u32_b32 v0, -1, v0
	ds_read_b64 v[2:3], v1
	v_mov_b32_e32 v1, s0
	ds_read_b64 v[4:5], v1
	v_and_b32_e32 v1, 63, v0
	v_lshlrev_b32_e32 v1, 2, v1
	s_waitcnt lgkmcnt(1)
	v_readfirstlane_b32 s14, v3
	v_readfirstlane_b32 s16, v2
	s_waitcnt lgkmcnt(0)
	v_readfirstlane_b32 s1, v5
	v_readfirstlane_b32 s0, v4
	v_add_u32_e32 v200, s66, v0
	s_mov_b32 s40, 9
	v_readfirstlane_b32 s3, v200
	s_nop 1
	global_load_dword v6, v1, s[0:1]
	s_add_i32 s0, 0, 0x20450
	v_mov_b32_e32 v4, s0
	ds_read_b64 v[4:5], v4
	s_waitcnt lgkmcnt(0)
	v_readfirstlane_b32 s1, v5
	v_readfirstlane_b32 s0, v4
	s_nop 4
	global_load_dword v7, v1, s[0:1]
	s_add_i32 s0, 0, 0x20458
	v_mov_b32_e32 v4, s0
	ds_read_b64 v[4:5], v4
	s_waitcnt lgkmcnt(0)
	v_readfirstlane_b32 s1, v5
	v_readfirstlane_b32 s0, v4
	s_waitcnt vmcnt(0)
	v_mul_f32_e32 v16, v6, v7
	s_nop 2
	global_load_dword v8, v1, s[0:1]
	s_add_i32 s0, 0, 0x20460
	v_mov_b32_e32 v4, s0
	ds_read_b64 v[4:5], v4
	s_waitcnt lgkmcnt(0)
	v_readfirstlane_b32 s1, v5
	v_readfirstlane_b32 s0, v4
	v_mbcnt_hi_u32_b32 v4, -1, v147
	v_and_b32_e32 v226, 64, v4
	v_xor_b32_e32 v5, 1, v4
	v_add_u32_e32 v15, 64, v226
	v_cmp_lt_i32_e32 vcc, v5, v15
	global_load_dword v1, v1, s[0:1]
	v_xor_b32_e32 v9, 2, v4
	v_cndmask_b32_e32 v5, v4, v5, vcc
	v_lshlrev_b32_e32 v5, 2, v5
	ds_bpermute_b32 v16, v5, v16
	v_cmp_lt_i32_e32 vcc, v9, v15
	v_xor_b32_e32 v10, 4, v4
	v_xor_b32_e32 v11, 8, v4
	v_cndmask_b32_e32 v9, v4, v9, vcc
	v_lshlrev_b32_e32 v9, 2, v9
	s_waitcnt lgkmcnt(0)
	v_fmac_f32_e32 v16, v6, v7
	ds_bpermute_b32 v6, v9, v16
	v_cmp_lt_i32_e32 vcc, v10, v15
	v_xor_b32_e32 v12, 16, v4
	v_xor_b32_e32 v13, 32, v4
	v_cndmask_b32_e32 v10, v4, v10, vcc
	v_lshlrev_b32_e32 v7, 2, v10
	s_waitcnt lgkmcnt(0)
	v_add_f32_e32 v6, v16, v6
	v_cmp_lt_i32_e32 vcc, v11, v15
	s_add_i32 s0, 0, 0x20468
	v_mov_b32_e32 v14, s0
	v_cndmask_b32_e32 v11, v4, v11, vcc
	v_cmp_lt_i32_e32 vcc, v12, v15
	s_cmpk_lg_i32 s33, 0x100
	s_cselect_b64 s[4:5], -1, 0
	v_cndmask_b32_e32 v12, v4, v12, vcc
	v_cmp_lt_i32_e32 vcc, v13, v15
	v_lshlrev_b32_e32 v205, 2, v12
	s_cmpk_eq_i32 s33, 0x100
	v_cndmask_b32_e32 v4, v4, v13, vcc
	v_lshlrev_b32_e32 v225, 2, v4
	s_waitcnt vmcnt(0)
	v_mul_f32_e32 v17, v8, v1
	ds_bpermute_b32 v5, v5, v17
	s_waitcnt lgkmcnt(0)
	v_fmac_f32_e32 v5, v8, v1
	ds_bpermute_b32 v1, v9, v5
	ds_bpermute_b32 v9, v7, v6
	v_lshlrev_b32_e32 v8, 2, v11
	s_waitcnt lgkmcnt(1)
	v_add_f32_e32 v1, v5, v1
	ds_bpermute_b32 v5, v7, v1
	s_waitcnt lgkmcnt(1)
	v_add_f32_e32 v4, v6, v9
	ds_bpermute_b32 v9, v8, v4
	ds_read_b64 v[6:7], v14
	s_waitcnt lgkmcnt(2)
	v_add_f32_e32 v1, v1, v5
	ds_bpermute_b32 v5, v8, v1
	s_waitcnt lgkmcnt(2)
	v_add_f32_e32 v3, v4, v9
	ds_bpermute_b32 v4, v205, v3
	s_waitcnt lgkmcnt(2)
	v_readfirstlane_b32 s1, v7
	v_readfirstlane_b32 s0, v6
	s_waitcnt lgkmcnt(1)
	v_add_f32_e32 v5, v1, v5
	ds_bpermute_b32 v8, v205, v5
	s_waitcnt lgkmcnt(1)
	v_add_f32_e32 v1, v3, v4
	ds_bpermute_b32 v2, v225, v1
	s_waitcnt lgkmcnt(1)
	v_add_f32_e32 v3, v5, v8
	ds_bpermute_b32 v4, v225, v3
	s_cbranch_scc1 .LBB0_719
	s_abs_i32 s6, s33
	v_cvt_f32_u32_e32 v5, s6
	s_sub_i32 s9, 0, s6
	s_add_i32 s7, s33, 0x83f
	s_xor_b32 s8, s7, s33
	v_rcp_iflag_f32_e32 v5, v5
	s_abs_i32 s7, s7
	s_ashr_i32 s8, s8, 31
	v_mul_f32_e32 v5, 0x4f7ffffe, v5
	v_cvt_u32_f32_e32 v5, v5
	s_nop 0
	v_readfirstlane_b32 s10, v5
	s_mul_i32 s9, s9, s10
	s_mul_hi_u32 s9, s10, s9
	s_add_i32 s10, s10, s9
	s_mul_hi_u32 s9, s7, s10
	s_mul_i32 s10, s9, s6
	s_sub_i32 s7, s7, s10
	s_add_i32 s11, s9, 1
	s_sub_i32 s10, s7, s6
	s_cmp_ge_u32 s7, s6
	s_cselect_b32 s9, s11, s9
	s_cselect_b32 s7, s10, s7
	s_add_i32 s10, s9, 1
	s_cmp_ge_u32 s7, s6
	s_cselect_b32 s6, s10, s9
	s_xor_b32 s6, s6, s8
	s_sub_i32 s40, s6, s8

; #define LAS __attribute__((address_space(3)))
; __device__ __forceinline__ unsigned xb_add(unsigned* p, unsigned v) { return __hip_atomic_fetch_add(p, v, __ATOMIC_RELAXED, __HIP_MEMORY_SCOPE_AGENT); }
; __device__ __forceinline__ void xcd_barrier(unsigned* bar, const unsigned x, volatile LAS unsigned* st, const bool leader) {
;     asm volatile("s_waitcnt vmcnt(0)" ::: "memory");
;     __syncthreads();
;     if (leader) {
;         __builtin_amdgcn_s_waitcnt(0);
;         unsigned nloc = st[0], nx = st[1];
;         if (nloc == 0u) { xcd_barrier_complete(bar, x, nloc, nx); st[0] = nloc; st[1] = nx; }
;         const unsigned old = xb_add(&bar[XB_XSUB(x)], 1u);
.LBB0_867:
	s_setprio 0
	s_add_i32 s0, 0, 0x204d0
	v_mov_b32_e32 v0, s0
	ds_read_b64 v[0:1], v0
	s_waitcnt lgkmcnt(2)
	v_mbcnt_lo_u32_b32 v2, -1, 0
	v_mbcnt_hi_u32_b32 v2, -1, v2
	s_waitcnt vmcnt(0)
	s_waitcnt lgkmcnt(0)
	v_cmp_eq_u32_e32 vcc, s67, v2
	v_readfirstlane_b32 s5, v1
	v_readfirstlane_b32 s4, v0
	s_barrier
	s_and_saveexec_b64 s[0:1], vcc
	s_cbranch_execz .LBB0_919
	s_add_i32 s3, 0, 0x20500
	v_mov_b32_e32 v0, s3
	s_waitcnt vmcnt(0) expcnt(0) lgkmcnt(0)
	ds_read_b32 v2, v0
	s_add_i32 s3, 0, 0x20504
	v_mov_b32_e32 v0, s3
	ds_read_b32 v0, v0
	s_waitcnt lgkmcnt(1)
	v_cmp_ne_u32_e32 vcc, 0, v2
	s_cbranch_vccnz .LBB0_883
	s_add_u32 s6, s4, 0x1000
	s_addc_u32 s7, s5, 0
	s_add_u32 s8, s4, 0x1100
	s_addc_u32 s9, s5, 0
	s_add_u32 s10, s4, 0x1200
	s_addc_u32 s11, s5, 0
	s_add_u32 s12, s4, 0x1300
	s_addc_u32 s13, s5, 0
	s_mov_b32 s3, 1
	v_mov_b32_e32 v16, 0
	s_branch .LBB0_871
